# v46 + the seven K-loop steady bodies and the MLA steady step aligned to 64 bytes (s_nop padding)
# speedup vs baseline: 1.0071x; 1.0071x over previous
.LBB0_495:
	s_ashr_i32 s13, s12, 31
	s_lshl_b64 s[14:15], s[12:13], 19
	v_readlane_b32 s16, v244, 44
	v_readlane_b32 s17, v244, 45
	s_add_u32 s14, s16, s14
	s_addc_u32 s15, s17, s15
	s_and_b64 s[40:41], s[6:7], exec
	s_cselect_b32 s13, s15, s57
	s_cselect_b32 s81, s14, s56
	s_ashr_i32 s11, s10, 31
	s_lshl_b64 s[40:41], s[10:11], 19
	s_add_u32 s40, s38, s40
	s_addc_u32 s41, s39, s41
	s_and_b64 s[42:43], s[6:7], exec
	s_cselect_b32 s11, s41, s59
	s_cselect_b32 s82, s40, s58
	s_lshl_b32 s42, s80, 10
	s_lshl_b32 s60, s12, 8
	s_add_i32 s83, s42, 0
	s_ashr_i32 s61, s60, 31
	s_add_i32 s83, s83, 0x20800
	s_add_u32 s56, s56, 0x40080
	s_addc_u32 s57, s57, 0
	s_add_u32 s84, s58, 0x100
	v_add_u32_e32 v245, 0x10000, v156
	v_add_u32_e32 v246, 0x10000, v157
	s_mov_b32 s100, 1
	s_addc_u32 s85, s59, 0
	s_mov_b32 s86, -2
	v_lshl_add_u64 v[148:149], s[60:61], 2, v[132:133]
	s_branch .LBB0_497
	.p2alignl 6, 3212836864

.LBB0_588:
	s_add_u32 s40, s40, 0xb0080
	s_addc_u32 s41, s41, 0
	s_add_u32 s42, s52, 0x100
	v_add_u32_e32 v245, 0x10000, v210
	v_add_u32_e32 v246, 0x10000, v211
	s_mov_b32 s100, 1
	s_addc_u32 s43, s53, 0
	s_mov_b32 s44, -2
	.p2alignl 6, 3212836864

.LBB0_683:
	s_ashr_i32 s5, s4, 31
	s_lshl_b64 s[38:39], s[4:5], 19
	v_readlane_b32 s16, v244, 44
	v_readlane_b32 s17, v244, 45
	s_add_u32 s72, s16, s38
	s_addc_u32 s73, s17, s39
	s_and_b64 s[38:39], s[6:7], exec
	s_cselect_b32 s5, s73, s11
	s_cselect_b32 s38, s72, s10
	s_ashr_i32 s13, s12, 31
	s_lshl_b64 s[42:43], s[12:13], 19
	s_add_u32 s70, s3, s42
	s_addc_u32 s71, s34, s43
	s_and_b64 s[42:43], s[6:7], exec
	s_cselect_b32 s13, s71, s87
	s_cselect_b32 s39, s70, s86
	s_lshl_b32 s44, s52, 10
	s_lshl_b32 s42, s4, 8
	s_add_i32 s53, s44, 0
	s_ashr_i32 s43, s42, 31
	s_add_i32 s53, s53, 0x20800
	s_add_u32 s10, s10, 0x40080
	s_addc_u32 s11, s11, 0
	s_add_u32 s68, s86, 0x100
	v_add_u32_e32 v245, 0x10000, v213
	v_add_u32_e32 v246, 0x10000, v214
	s_mov_b32 s100, 1
	s_waitcnt vmcnt(0)
	v_lshl_add_u64 v[130:131], s[42:43], 2, v[172:173]
	s_addc_u32 s69, s87, 0
	v_readfirstlane_b32 s101, v0
	s_bfe_u32 s101, s101, 0x20006
	s_cmp_eq_u32 s14, 1
	s_cselect_b32 s101, s101, 0
	s_mov_b32 s42, -2
	s_branch .LBB0_685
	.p2alignl 6, 3212836864

.LBB0_1315:
	s_lshl_b32 s44, s66, 10
	s_lshl_b32 s42, s67, 8
	s_add_i32 s69, s44, 0
	s_add_i32 s68, s39, -2
	s_ashr_i32 s43, s42, 31
	s_add_i32 s69, s69, 0x20800
	s_cmp_lt_i32 s28, 3
	s_cselect_b32 s44, s93, s61
	s_cselect_b32 s45, s92, s60
	s_lshl_b64 s[42:43], s[42:43], 2
	s_add_u32 s42, s45, s42
	s_addc_u32 s43, s44, s43
	s_add_u32 s12, s12, 0x18080
	s_addc_u32 s13, s13, 0
	s_add_u32 s48, s78, 0x100
	v_add_u32_e32 v245, 0x10000, v209
	v_add_u32_e32 v246, 0x10000, v210
	s_mov_b32 s100, 1
	v_lshl_add_u64 v[130:131], s[42:43], 0, v[188:189]
	s_addc_u32 s72, s79, 0
	s_mov_b32 s42, 0
	s_branch .LBB0_1317
	.p2alignl 6, 3212836864

.LBB0_1475:
	s_add_u32 s0, s34, s18
	s_addc_u32 s24, s35, s19
	s_lshl_b64 s[22:23], s[22:23], 1
	s_add_u32 s22, s0, s22
	s_addc_u32 s23, s24, s23
	s_lshl_b32 s25, s51, 13
	s_add_i32 s25, s25, s43
	s_mov_b32 s52, m0
	s_mov_b32 m0, s25
	s_nop 0
	global_load_lds_dwordx4 v181, s[22:23]
	s_mov_b32 m0, s52
	s_waitcnt lgkmcnt(11)
	v_mfma_f32_32x32x16_bf16 v[34:49], v[94:97], v[98:101], v[18:33]
	s_waitcnt lgkmcnt(10)
	v_mfma_f32_32x32x16_bf16 v[18:33], v[86:89], v[98:101], v[18:33]
	s_waitcnt lgkmcnt(9)
	v_mfma_f32_32x32x16_bf16 v[34:49], v[90:93], v[106:109], v[34:49]
	s_waitcnt lgkmcnt(8)
	v_mfma_f32_32x32x16_bf16 v[18:33], v[82:85], v[106:109], v[18:33]
	s_waitcnt lgkmcnt(7)
	v_mfma_f32_32x32x16_bf16 v[34:49], v[78:81], v[102:105], v[34:49]
	s_waitcnt lgkmcnt(6)
	v_mfma_f32_32x32x16_bf16 v[18:33], v[74:77], v[102:105], v[18:33]
	s_waitcnt lgkmcnt(5)
	v_mfma_f32_32x32x16_bf16 v[34:49], v[70:73], v[114:117], v[34:49]
	s_waitcnt lgkmcnt(4)
	v_mfma_f32_32x32x16_bf16 v[18:33], v[66:69], v[114:117], v[18:33]
	s_waitcnt lgkmcnt(3)
	v_mfma_f32_32x32x16_bf16 v[34:49], v[62:65], v[110:113], v[34:49]
	v_lshl_add_u32 v62, s49, 13, v183
	ds_read_b64_tr_b16 v[94:95], v62 offset:24576
	ds_read_b64_tr_b16 v[96:97], v62 offset:25088
	ds_read_b64_tr_b16 v[90:91], v62 offset:25600
	ds_read_b64_tr_b16 v[92:93], v62 offset:26112
	ds_read_b64_tr_b16 v[86:87], v62 offset:26624
	ds_read_b64_tr_b16 v[88:89], v62 offset:27136
	ds_read_b64_tr_b16 v[82:83], v62 offset:27648
	ds_read_b64_tr_b16 v[84:85], v62 offset:28160
	ds_read_b64_tr_b16 v[78:79], v62 offset:28672
	ds_read_b64_tr_b16 v[80:81], v62 offset:29184
	ds_read_b64_tr_b16 v[74:75], v62 offset:29696
	ds_read_b64_tr_b16 v[76:77], v62 offset:30208
	ds_read_b64_tr_b16 v[70:71], v62 offset:30720
	ds_read_b64_tr_b16 v[72:73], v62 offset:31232
	ds_read_b64_tr_b16 v[66:67], v62 offset:31744
	ds_read_b64_tr_b16 v[68:69], v62 offset:32256
	s_waitcnt lgkmcnt(14)
	v_mfma_f32_32x32x16_bf16 v[18:33], v[58:61], v[110:113], v[18:33]
	v_mfma_f32_32x32x16_bf16 v[34:49], v[54:57], v[118:121], v[34:49]
	v_mfma_f32_32x32x16_bf16 v[18:33], v[50:53], v[118:121], v[18:33]
	s_nop 10
	v_max_f32_e32 v50, v35, v35
	v_max_f32_e32 v51, v34, v34
	v_max_f32_e32 v50, v51, v50
	v_max3_f32 v51, v36, v37, v19
	v_max3_f32 v50, v50, v18, v20
	v_max3_f32 v50, v50, v21, v38
	v_max3_f32 v51, v51, v40, v41
	v_max3_f32 v50, v50, v39, v22
	v_max3_f32 v51, v51, v24, v25
	v_max3_f32 v50, v50, v23, v42
	v_max3_f32 v51, v51, v44, v45
	v_max3_f32 v50, v50, v43, v26
	v_max3_f32 v51, v51, v28, v29
	v_max3_f32 v50, v50, v27, v46
	v_max3_f32 v51, v51, v48, v49
	v_max3_f32 v50, v50, v47, v30
	v_max3_f32 v51, v51, v32, v33
	v_max3_f32 v50, v50, v31, v51
	v_mov_b32_e32 v51, v50
	s_nop 1
	v_permlane32_swap_b32_e32 v50, v51
	v_max_f32_e32 v51, v51, v51
	v_max_f32_e32 v50, v50, v50
	v_max_f32_e32 v122, v50, v51
	v_sub_f32_e32 v18, v18, v122
	v_sub_f32_e32 v19, v19, v122
	v_sub_f32_e32 v34, v34, v122
	v_sub_f32_e32 v35, v35, v122
	v_exp_f32_e32 v34, v34
	v_exp_f32_e32 v127, v18
	v_exp_f32_e32 v18, v35
	v_exp_f32_e32 v128, v19
	v_sub_f32_e32 v20, v20, v122
	v_sub_f32_e32 v36, v36, v122
	v_exp_f32_e32 v19, v36
	v_exp_f32_e32 v129, v20
	v_sub_f32_e32 v21, v21, v122
	v_sub_f32_e32 v22, v22, v122
	v_sub_f32_e32 v23, v23, v122
	v_sub_f32_e32 v24, v24, v122
	v_sub_f32_e32 v25, v25, v122
	v_sub_f32_e32 v37, v37, v122
	v_sub_f32_e32 v38, v38, v122
	v_sub_f32_e32 v39, v39, v122
	v_sub_f32_e32 v40, v40, v122
	v_sub_f32_e32 v41, v41, v122
	v_exp_f32_e32 v20, v37
	v_exp_f32_e32 v130, v21
	v_exp_f32_e32 v21, v38
	v_exp_f32_e32 v38, v22
	v_exp_f32_e32 v22, v39
	v_exp_f32_e32 v39, v23
	v_exp_f32_e32 v23, v40
	v_exp_f32_e32 v40, v24
	v_exp_f32_e32 v131, v25
	v_add_f32_e32 v24, v34, v18
	v_add_f32_e32 v25, v127, v128
	v_exp_f32_e32 v41, v41
	v_cvt_pk_bf16_f32 v34, v34, v18
	v_add_f32_e32 v24, v24, v19
	v_add_f32_e32 v25, v25, v129
	v_cvt_pk_bf16_f32 v35, v19, v20
	v_add_f32_e32 v24, v24, v20
	v_add_f32_e32 v25, v25, v130
	v_cvt_pk_bf16_f32 v36, v21, v22
	v_cvt_pk_bf16_f32 v37, v23, v41
	v_add_f32_e32 v24, v21, v24
	v_add_f32_e32 v25, v38, v25
	v_sub_f32_e32 v42, v42, v122
	v_sub_f32_e32 v43, v43, v122
	v_sub_f32_e32 v44, v44, v122
	v_sub_f32_e32 v45, v45, v122
	v_sub_f32_e32 v46, v46, v122
	v_sub_f32_e32 v47, v47, v122
	v_sub_f32_e32 v48, v48, v122
	v_sub_f32_e32 v49, v49, v122
	v_add_f32_e32 v24, v22, v24
	v_add_f32_e32 v25, v39, v25
	v_sub_f32_e32 v26, v26, v122
	v_sub_f32_e32 v27, v27, v122
	v_sub_f32_e32 v28, v28, v122
	v_sub_f32_e32 v29, v29, v122
	v_sub_f32_e32 v30, v30, v122
	v_sub_f32_e32 v31, v31, v122
	v_sub_f32_e32 v32, v32, v122
	v_sub_f32_e32 v33, v33, v122
	v_exp_f32_e32 v42, v42
	v_exp_f32_e32 v43, v43
	v_exp_f32_e32 v44, v44
	v_exp_f32_e32 v45, v45
	v_exp_f32_e32 v136, v46
	v_exp_f32_e32 v138, v47
	v_exp_f32_e32 v140, v48
	v_exp_f32_e32 v142, v49
	v_exp_f32_e32 v132, v26
	v_exp_f32_e32 v133, v27
	v_exp_f32_e32 v134, v28
	v_exp_f32_e32 v135, v29
	v_exp_f32_e32 v137, v30
	v_exp_f32_e32 v139, v31
	v_exp_f32_e32 v141, v32
	v_exp_f32_e32 v143, v33
	v_add_f32_e32 v46, v23, v24
	v_add_f32_e32 v47, v40, v25
	v_mfma_f32_32x32x16_bf16 v[18:33], v[34:37], v[94:97], 0
	v_add_f32_e32 v171, 0, v122
	v_exp_f32_e64 v126, -v122
	v_cvt_pk_bf16_f32 v122, v42, v43
	v_cvt_pk_bf16_f32 v123, v44, v45
	v_cvt_pk_bf16_f32 v124, v136, v138
	v_cvt_pk_bf16_f32 v125, v140, v142
	v_cvt_pk_bf16_f32 v94, v127, v128
	v_cvt_pk_bf16_f32 v95, v129, v130
	s_waitcnt lgkmcnt(12)
	v_mfma_f32_32x32x16_bf16 v[18:33], v[122:125], v[90:93], v[18:33]
	v_cvt_pk_bf16_f32 v96, v38, v39
	v_cvt_pk_bf16_f32 v97, v40, v131
	v_cvt_pk_bf16_f32 v90, v132, v133
	v_add_f32_e32 v41, v41, v46
	s_waitcnt lgkmcnt(10)
	v_mfma_f32_32x32x16_bf16 v[18:33], v[94:97], v[86:89], v[18:33]
	v_add_f32_e32 v38, v42, v41
	v_add_f32_e32 v46, v131, v47
	v_cvt_pk_bf16_f32 v91, v134, v135
	v_cvt_pk_bf16_f32 v92, v137, v139
	v_cvt_pk_bf16_f32 v93, v141, v143
	v_add_f32_e32 v38, v43, v38
	v_add_f32_e32 v39, v132, v46
	s_waitcnt lgkmcnt(8)
	v_mfma_f32_32x32x16_bf16 v[18:33], v[90:93], v[82:85], v[18:33]
	v_add_f32_e32 v39, v133, v39
	v_add_f32_e32 v38, v44, v38
	s_lshl_b64 s[22:23], s[14:15], 6
	v_add_f32_e32 v82, v134, v39
	v_add_f32_e32 v83, v45, v38
	s_waitcnt lgkmcnt(6)
	v_mfma_f32_32x32x16_bf16 v[34:49], v[34:37], v[78:81], 0
	s_add_u32 s22, s13, s22
	v_add_f32_e32 v78, v135, v82
	v_add_f32_e32 v79, v136, v83
	v_add_f32_e32 v78, v137, v78
	s_waitcnt lgkmcnt(4)
	v_mfma_f32_32x32x16_bf16 v[34:49], v[122:125], v[74:77], v[34:49]
	v_xor_b32_e32 v50, 0x80000000, v171
	v_add_f32_e32 v74, v138, v79
	v_add_f32_e32 v75, v139, v78
	s_waitcnt lgkmcnt(2)
	v_mfma_f32_32x32x16_bf16 v[34:49], v[94:97], v[70:73], v[34:49]
	v_add_f32_e32 v74, v140, v74
	v_add_f32_e32 v75, v141, v75
	s_addc_u32 s23, s46, s23
	s_lshl_b64 s[54:55], s[14:15], 10
	v_mov_b32_e32 v51, v50
	v_mov_b32_e32 v52, v50
	v_mov_b32_e32 v53, v50
	s_waitcnt lgkmcnt(0)
	v_mfma_f32_32x32x16_bf16 v[34:49], v[90:93], v[66:69], v[34:49]
	v_mov_b32_e32 v54, v50
	v_mov_b32_e32 v55, v50
	v_mov_b32_e32 v56, v50
	v_mov_b32_e32 v57, v50
	v_mov_b32_e32 v58, v50
	v_mov_b32_e32 v59, v50
	v_mov_b32_e32 v60, v50
	v_mov_b32_e32 v61, v50
	v_mov_b32_e32 v62, v50
	v_mov_b32_e32 v63, v50
	v_mov_b32_e32 v64, v50
	v_mov_b32_e32 v65, v50
	s_add_u32 s0, s0, s54
	v_add_f32_e32 v70, v142, v74
	v_add_f32_e32 v71, v143, v75
	s_waitcnt vmcnt(0) lgkmcnt(0)
	s_barrier
	s_addc_u32 s53, s24, s55
	v_add_f32_e32 v173, v70, v71
	s_add_u32 s54, s26, s54
	v_fmac_f32_e32 v173, 0, v126
	s_addc_u32 s55, s27, s55
	s_mov_b64 s[24:25], 0x20000
	s_mov_b32 s49, s51
	.p2alignl 6, 3212836864

.LBB0_1628:
	s_ashr_i32 s15, s14, 31
	s_lshl_b64 s[16:17], s[14:15], 19
	s_add_u32 s16, s3, s16
	s_addc_u32 s17, s90, s17
	s_and_b64 s[18:19], s[6:7], exec
	s_cselect_b32 s15, s17, s25
	s_cselect_b32 s21, s16, s24
	s_ashr_i32 s13, s12, 31
	s_lshl_b64 s[18:19], s[12:13], 19
	s_add_u32 s18, s38, s18
	s_addc_u32 s19, s39, s19
	s_and_b64 s[28:29], s[6:7], exec
	s_cselect_b32 s13, s19, s27
	s_cselect_b32 s23, s18, s26
	s_add_u32 s24, s24, 0x40080
	s_addc_u32 s25, s25, 0
	s_add_u32 s55, s26, 0x100
	v_add_u32_e32 v245, 0x10000, v209
	v_add_u32_e32 v246, 0x10000, v210
	s_mov_b32 s100, 1
	s_addc_u32 s56, s27, 0
	s_mov_b32 s57, -2
	s_waitcnt vmcnt(0)
	.p2alignl 6, 3212836864

.LBB0_1720:
	s_ashr_i32 s13, s12, 31
	s_lshl_b64 s[14:15], s[12:13], 19
	s_add_u32 s14, s80, s14
	s_addc_u32 s15, s81, s15
	s_and_b64 s[16:17], s[6:7], exec
	s_cselect_b32 s13, s15, s23
	s_cselect_b32 s58, s14, s22
	s_ashr_i32 s5, s4, 31
	s_lshl_b64 s[16:17], s[4:5], 19
	s_add_u32 s16, s28, s16
	s_addc_u32 s17, s29, s17
	s_and_b64 s[26:27], s[6:7], exec
	s_cselect_b32 s5, s17, s25
	s_cselect_b32 s59, s16, s24
	s_lshl_b32 s60, s57, 10
	s_lshl_b32 s26, s12, 8
	s_add_i32 s60, s60, 0
	s_ashr_i32 s27, s26, 31
	s_add_i32 s60, s60, 0x20800
	s_add_u32 s22, s22, 0x40080
	s_addc_u32 s23, s23, 0
	s_add_u32 s61, s24, 0x100
	v_add_u32_e32 v245, 0x10000, v155
	v_add_u32_e32 v246, 0x10000, v156
	s_mov_b32 s100, 1
	v_lshl_add_u64 v[148:149], s[26:27], 2, v[138:139]
	s_addc_u32 s62, s25, 0
	s_mov_b32 s63, -2
	s_branch .LBB0_1722
	.p2alignl 6, 3212836864

.LBB0_1826:
	s_add_u32 s4, s42, 0xb0080
	s_addc_u32 s5, s43, 0
	s_add_u32 s64, s40, 0x100
	v_add_u32_e32 v245, 0x10000, v218
	v_add_u32_e32 v246, 0x10000, v219
	s_mov_b32 s100, 1
	s_addc_u32 s65, s41, 0
	s_mov_b32 s66, -2
	s_waitcnt lgkmcnt(0)
	s_waitcnt vmcnt(0)
	.p2alignl 6, 3212836864
